# LayerNorm k5 loop: next iteration's rows prefetched into a second register set
# speedup vs baseline: 1.0004x; 1.0004x over previous
.LBB0_141:
	s_andn2_b64 vcc, exec, s[28:29]
	s_cbranch_vccnz .LBB0_228
	s_cmp_gt_i32 s25, 4
	s_mov_b64 s[0:1], -1
	s_cbranch_scc0 .LBB0_152
	v_mov_b32_e32 v0, v169
	s_waitcnt vmcnt(7)
	v_mov_b32_e32 v2, v169
	v_readlane_b32 s0, v254, 32
	s_nop 1
	v_add_u32_e32 v2, s0, v2
	s_mov_b32 s0, 0x200000
	v_cmp_gt_u32_e32 vcc, s0, v2
	s_and_saveexec_b64 s[28:29], vcc
	s_cbranch_execz .LBB0_151
	s_load_dword s0, s[22:23], 0x0
	v_lshrrev_b32_e32 v44, 6, v2
	v_and_b32_e32 v2, 63, v0
	v_readlane_b32 s44, v253, 18
	v_lshlrev_b32_e32 v0, 4, v2
	v_readlane_b32 s58, v253, 32
	v_readlane_b32 s59, v253, 33
	s_waitcnt lgkmcnt(0)
	s_lshl_b32 s42, s0, 2
	v_readlane_b32 s0, v254, 28
	v_lshl_add_u64 v[34:35], s[58:59], 0, v[0:1]
	v_lshl_add_u64 v[36:37], s[34:35], 0, v[0:1]
	v_lshl_add_u64 v[38:39], s[40:41], 0, v[0:1]
	v_lshlrev_b32_e32 v0, 3, v2
	v_readlane_b32 s1, v254, 29
	v_cmp_eq_u32_e32 vcc, 0, v2
	s_ashr_i32 s43, s42, 31
	v_lshl_add_u64 v[40:41], s[0:1], 0, v[0:1]
	v_cmp_lt_i32_e64 s[0:1], v184, v183
	s_mov_b64 s[34:35], 0
	v_readlane_b32 s45, v253, 19
	v_cndmask_b32_e64 v0, v182, v184, s[0:1]
	v_cmp_lt_i32_e64 s[0:1], v185, v183
	v_lshlrev_b32_e32 v50, 2, v0
	v_readlane_b32 s46, v253, 20
	v_cndmask_b32_e64 v0, v182, v185, s[0:1]
	v_lshlrev_b32_e32 v51, 2, v0
	v_xor_b32_e32 v0, 8, v182
	v_cmp_lt_i32_e64 s[0:1], v0, v183
	v_readlane_b32 s47, v253, 21
	v_readlane_b32 s48, v253, 22
	v_cndmask_b32_e64 v0, v182, v0, s[0:1]
	v_lshlrev_b32_e32 v52, 2, v0
	v_xor_b32_e32 v0, 4, v182
	v_cmp_lt_i32_e64 s[0:1], v0, v183
	v_readlane_b32 s49, v253, 23
	v_readlane_b32 s50, v253, 24
	v_cndmask_b32_e64 v0, v182, v0, s[0:1]
	v_lshlrev_b32_e32 v53, 2, v0
	v_xor_b32_e32 v0, 2, v182
	v_cmp_lt_i32_e64 s[0:1], v0, v183
	v_readlane_b32 s51, v253, 25
	v_readlane_b32 s52, v253, 26
	v_cndmask_b32_e64 v0, v182, v0, s[0:1]
	v_lshlrev_b32_e32 v54, 2, v0
	v_xor_b32_e32 v0, 1, v182
	v_cmp_lt_i32_e64 s[0:1], v0, v183
	v_readlane_b32 s53, v253, 27
	v_readlane_b32 s54, v253, 28
	v_cndmask_b32_e64 v0, v182, v0, s[0:1]
	v_lshlrev_b32_e32 v55, 2, v0
	v_readlane_b32 s55, v253, 29
	v_readlane_b32 s56, v253, 30
	v_readlane_b32 s57, v253, 31
	global_load_dwordx4 v[100:103], v[36:37], off
	global_load_dwordx4 v[116:119], v[38:39], off
	global_load_dwordx4 v[104:107], v[36:37], off offset:1024
	global_load_dwordx4 v[120:123], v[38:39], off offset:1024
	global_load_dwordx4 v[108:111], v[36:37], off offset:2048
	global_load_dwordx4 v[124:127], v[38:39], off offset:2048
	global_load_dwordx4 v[112:115], v[36:37], off offset:3072
	global_load_dwordx4 v[128:131], v[38:39], off offset:3072
	s_waitcnt vmcnt(0)
	v_add_u32_e32 v166, s42, v44
	s_movk_i32 s98, 0x7fff
	v_cmp_ge_i32_e64 s[100:101], s98, v166
	s_nop 1
	v_cndmask_b32_e64 v166, v44, v166, s[100:101]
	v_ashrrev_i32_e32 v165, 31, v44
	v_mov_b32_e32 v164, v44
	v_ashrrev_i32_e32 v167, 31, v166
	v_lshlrev_b64 v[164:165], 12, v[164:165]
	v_lshlrev_b64 v[166:167], 12, v[166:167]
	v_lshl_add_u64 v[164:165], v[34:35], 0, v[164:165]
	v_lshl_add_u64 v[166:167], v[34:35], 0, v[166:167]
	global_load_dwordx4 v[132:135], v[164:165], off
	global_load_dwordx4 v[136:139], v[164:165], off offset:1024
	global_load_dwordx4 v[140:143], v[164:165], off offset:2048
	global_load_dwordx4 v[144:147], v[164:165], off offset:3072
	global_load_dwordx4 v[148:151], v[166:167], off
	global_load_dwordx4 v[152:155], v[166:167], off offset:1024
	global_load_dwordx4 v[156:159], v[166:167], off offset:2048
	global_load_dwordx4 v[160:163], v[166:167], off offset:3072
	s_waitcnt vmcnt(0)
	s_branch .LBB0_146

.LBB0_146:
	v_add_u32_e32 v42, s42, v44
	s_mov_b32 s0, 0x8000
	v_cmp_gt_i32_e64 s[38:39], s0, v42
	v_ashrrev_i32_e32 v45, 31, v44
	v_lshlrev_b64 v[2:3], 12, v[44:45]
	v_cndmask_b32_e64 v4, v44, v42, s[38:39]
	v_ashrrev_i32_e32 v5, 31, v4
	v_lshlrev_b64 v[4:5], 12, v[4:5]
	v_lshl_add_u64 v[2:3], v[34:35], 0, v[2:3]
	v_lshl_add_u64 v[4:5], v[34:35], 0, v[4:5]
	s_waitcnt vmcnt(4)
	v_mov_b32_e32 v30, v132
	v_mov_b32_e32 v31, v133
	v_mov_b32_e32 v32, v134
	v_mov_b32_e32 v33, v135
	v_mov_b32_e32 v26, v136
	v_mov_b32_e32 v27, v137
	v_mov_b32_e32 v28, v138
	v_mov_b32_e32 v29, v139
	v_mov_b32_e32 v22, v140
	v_mov_b32_e32 v23, v141
	v_mov_b32_e32 v24, v142
	v_mov_b32_e32 v25, v143
	v_mov_b32_e32 v18, v144
	v_mov_b32_e32 v19, v145
	v_mov_b32_e32 v20, v146
	v_mov_b32_e32 v21, v147
	v_mov_b32_e32 v14, v148
	v_mov_b32_e32 v15, v149
	v_mov_b32_e32 v16, v150
	v_mov_b32_e32 v17, v151
	v_mov_b32_e32 v10, v152
	v_mov_b32_e32 v11, v153
	v_mov_b32_e32 v12, v154
	v_mov_b32_e32 v13, v155
	v_mov_b32_e32 v6, v156
	v_mov_b32_e32 v7, v157
	v_mov_b32_e32 v8, v158
	v_mov_b32_e32 v9, v159
	v_mov_b32_e32 v2, v160
	v_mov_b32_e32 v3, v161
	v_mov_b32_e32 v4, v162
	v_mov_b32_e32 v5, v163
	v_add_u32_e32 v164, s42, v42
	v_add_u32_e32 v166, s42, v164
	s_movk_i32 s98, 0x7fff
	v_cmp_ge_i32_e64 s[100:101], s98, v164
	s_nop 1
	v_cndmask_b32_e64 v164, v44, v164, s[100:101]
	v_cmp_ge_i32_e64 s[100:101], s98, v166
	s_nop 1
	v_cndmask_b32_e64 v166, v164, v166, s[100:101]
	v_ashrrev_i32_e32 v165, 31, v164
	v_ashrrev_i32_e32 v167, 31, v166
	v_lshlrev_b64 v[164:165], 12, v[164:165]
	v_lshlrev_b64 v[166:167], 12, v[166:167]
	v_lshl_add_u64 v[164:165], v[34:35], 0, v[164:165]
	v_lshl_add_u64 v[166:167], v[34:35], 0, v[166:167]
	global_load_dwordx4 v[132:135], v[164:165], off
	global_load_dwordx4 v[136:139], v[164:165], off offset:1024
	global_load_dwordx4 v[140:143], v[164:165], off offset:2048
	global_load_dwordx4 v[144:147], v[164:165], off offset:3072
	global_load_dwordx4 v[148:151], v[166:167], off
	global_load_dwordx4 v[152:155], v[166:167], off offset:1024
	global_load_dwordx4 v[156:159], v[166:167], off offset:2048
	global_load_dwordx4 v[160:163], v[166:167], off offset:3072
	s_mov_b32 s0, 0x3c800000
	s_mov_b32 s1, 0x3a800000
	s_mov_b32 s0, s1
	s_mov_b32 s2, 0x800000
	v_pk_add_f32 v[48:49], v[30:31], v[26:27]
	v_pk_add_f32 v[46:47], v[32:33], v[28:29]
	v_pk_add_f32 v[48:49], v[48:49], v[22:23]
	v_pk_add_f32 v[46:47], v[46:47], v[24:25]
	v_pk_add_f32 v[48:49], v[48:49], v[18:19]
	v_pk_add_f32 v[46:47], v[46:47], v[20:21]
	v_add_f32_e32 v0, v48, v49
	v_add_f32_e32 v0, v46, v0
	v_pk_add_f32 v[58:59], v[14:15], v[10:11]
	v_add_f32_e32 v0, v47, v0
	v_pk_add_f32 v[56:57], v[16:17], v[12:13]
	v_pk_add_f32 v[58:59], v[58:59], v[6:7]
	ds_bpermute_b32 v46, v50, v0
	v_pk_add_f32 v[56:57], v[56:57], v[8:9]
	v_pk_add_f32 v[58:59], v[58:59], v[2:3]
	v_pk_add_f32 v[56:57], v[56:57], v[4:5]
	v_add_f32_e32 v43, v58, v59
	v_add_f32_e32 v43, v56, v43
	v_add_f32_e32 v43, v57, v43
	s_waitcnt lgkmcnt(0)
	v_add_f32_e32 v0, v0, v46
	ds_bpermute_b32 v46, v50, v43
	s_waitcnt lgkmcnt(0)
	v_add_f32_e32 v43, v43, v46
	ds_bpermute_b32 v46, v51, v0
	s_waitcnt lgkmcnt(0)
	v_add_f32_e32 v0, v0, v46
	ds_bpermute_b32 v46, v51, v43
	s_waitcnt lgkmcnt(0)
	v_add_f32_e32 v43, v43, v46
	ds_bpermute_b32 v46, v52, v0
	s_waitcnt lgkmcnt(0)
	v_add_f32_e32 v0, v0, v46
	ds_bpermute_b32 v46, v52, v43
	s_waitcnt lgkmcnt(0)
	v_add_f32_e32 v43, v43, v46
	ds_bpermute_b32 v46, v53, v0
	s_waitcnt lgkmcnt(0)
	v_add_f32_e32 v0, v0, v46
	ds_bpermute_b32 v46, v53, v43
	s_waitcnt lgkmcnt(0)
	v_add_f32_e32 v43, v43, v46
	ds_bpermute_b32 v46, v54, v0
	s_waitcnt lgkmcnt(0)
	v_add_f32_e32 v0, v0, v46
	ds_bpermute_b32 v46, v54, v43
	s_waitcnt lgkmcnt(0)
	v_add_f32_e32 v43, v43, v46
	ds_bpermute_b32 v46, v55, v0
	s_waitcnt lgkmcnt(0)
	v_add_f32_e32 v46, v0, v46
	ds_bpermute_b32 v0, v55, v43
	v_fmamk_f32 v27, v46, 0xba800000, v27
	v_fmac_f32_e32 v26, 0xba800000, v46
	v_fmamk_f32 v31, v46, 0xba800000, v31
	v_fmac_f32_e32 v30, 0xba800000, v46
	s_waitcnt lgkmcnt(0)
	v_add_f32_e32 v43, v43, v0
	v_fmamk_f32 v11, v43, 0xba800000, v11
	v_fmac_f32_e32 v10, 0xba800000, v43
	v_fmamk_f32 v29, v46, 0xba800000, v29
	v_fmamk_f32 v28, v46, 0xba800000, v28
	v_fmamk_f32 v15, v43, 0xba800000, v15
	v_fmac_f32_e32 v14, 0xba800000, v43
	v_fmamk_f32 v13, v43, 0xba800000, v13
	v_fmamk_f32 v12, v43, 0xba800000, v12
	v_pk_mul_f32 v[48:49], v[26:27], v[26:27]
	v_pk_mul_f32 v[58:59], v[10:11], v[10:11]
	v_fmamk_f32 v33, v46, 0xba800000, v33
	v_fmamk_f32 v32, v46, 0xba800000, v32
	v_fmamk_f32 v23, v46, 0xba800000, v23
	v_fmac_f32_e32 v22, 0xba800000, v46
	v_fmamk_f32 v17, v43, 0xba800000, v17
	v_fmamk_f32 v16, v43, 0xba800000, v16
	v_fmamk_f32 v7, v43, 0xba800000, v7
	v_fmac_f32_e32 v6, 0xba800000, v43
	v_pk_mul_f32 v[56:57], v[28:29], v[28:29]
	v_pk_fma_f32 v[48:49], v[30:31], v[30:31], v[48:49]
	v_pk_mul_f32 v[60:61], v[12:13], v[12:13]
	v_pk_fma_f32 v[58:59], v[14:15], v[14:15], v[58:59]
	v_fmamk_f32 v25, v46, 0xba800000, v25
	v_fmamk_f32 v24, v46, 0xba800000, v24
	v_fmamk_f32 v19, v46, 0xba800000, v19
	v_fmac_f32_e32 v18, 0xba800000, v46
	v_fmamk_f32 v9, v43, 0xba800000, v9
	v_fmamk_f32 v8, v43, 0xba800000, v8
	v_fmamk_f32 v3, v43, 0xba800000, v3
	v_fmac_f32_e32 v2, 0xba800000, v43
	v_pk_fma_f32 v[56:57], v[32:33], v[32:33], v[56:57]
	v_pk_fma_f32 v[48:49], v[22:23], v[22:23], v[48:49]
	v_pk_fma_f32 v[60:61], v[16:17], v[16:17], v[60:61]
	v_pk_fma_f32 v[58:59], v[6:7], v[6:7], v[58:59]
	v_fmamk_f32 v21, v46, 0xba800000, v21
	v_fmamk_f32 v20, v46, 0xba800000, v20
	v_fmamk_f32 v5, v43, 0xba800000, v5
	v_fmamk_f32 v4, v43, 0xba800000, v4
	v_pk_fma_f32 v[56:57], v[24:25], v[24:25], v[56:57]
	v_pk_fma_f32 v[48:49], v[18:19], v[18:19], v[48:49]
	v_pk_fma_f32 v[60:61], v[8:9], v[8:9], v[60:61]
	v_pk_fma_f32 v[58:59], v[2:3], v[2:3], v[58:59]
	v_pk_fma_f32 v[56:57], v[20:21], v[20:21], v[56:57]
	v_pk_fma_f32 v[60:61], v[4:5], v[4:5], v[60:61]
	v_mov_b32_e32 v62, v58
	v_mov_b32_e32 v63, v48
	v_mov_b32_e32 v48, v59
	v_pk_add_f32 v[48:49], v[62:63], v[48:49]
	v_mov_b32_e32 v58, v60
	v_mov_b32_e32 v59, v56
	v_pk_add_f32 v[48:49], v[58:59], v[48:49]
	v_mov_b32_e32 v56, v61
	v_pk_add_f32 v[48:49], v[56:57], v[48:49]
	ds_bpermute_b32 v57, v50, v49
	ds_bpermute_b32 v56, v50, v48
	v_mov_b32_e32 v0, 0x3727c5ac
	s_waitcnt lgkmcnt(0)
	v_pk_add_f32 v[48:49], v[48:49], v[56:57]
	ds_bpermute_b32 v57, v51, v49
	ds_bpermute_b32 v56, v51, v48
	s_waitcnt lgkmcnt(0)
	v_pk_add_f32 v[48:49], v[48:49], v[56:57]
	ds_bpermute_b32 v57, v52, v49
	ds_bpermute_b32 v56, v52, v48
	s_waitcnt lgkmcnt(0)
	v_pk_add_f32 v[48:49], v[48:49], v[56:57]
	ds_bpermute_b32 v57, v53, v49
	ds_bpermute_b32 v56, v53, v48
	s_waitcnt lgkmcnt(0)
	v_pk_add_f32 v[48:49], v[48:49], v[56:57]
	ds_bpermute_b32 v57, v54, v49
	ds_bpermute_b32 v56, v54, v48
	s_waitcnt lgkmcnt(0)
	v_pk_add_f32 v[48:49], v[48:49], v[56:57]
	ds_bpermute_b32 v57, v55, v49
	ds_bpermute_b32 v56, v55, v48
	s_waitcnt lgkmcnt(0)
	v_pk_add_f32 v[48:49], v[48:49], v[56:57]
	s_nop 0
	v_pk_fma_f32 v[48:49], v[48:49], s[0:1], v[0:1] op_sel_hi:[1,0,0]
	s_nop 0
	v_mul_f32_e32 v0, 0x4b800000, v49
	v_cmp_gt_f32_e64 s[40:41], s2, v49
	v_cmp_gt_f32_e64 s[0:1], s2, v48
	s_nop 0
	v_cndmask_b32_e64 v0, v49, v0, s[40:41]
	v_rsq_f32_e32 v0, v0
	s_nop 0
	v_mul_f32_e32 v47, 0x45800000, v0
	v_cndmask_b32_e64 v0, v0, v47, s[40:41]
	v_mul_f32_e32 v47, 0x4b800000, v48
	v_cndmask_b32_e64 v47, v48, v47, s[0:1]
	v_rsq_f32_e32 v47, v47
	s_nop 0
	v_mul_f32_e32 v48, 0x45800000, v47
	v_cndmask_b32_e64 v47, v47, v48, s[0:1]
	s_and_saveexec_b64 s[0:1], vcc
	s_cbranch_execz .LBB0_149
	v_readlane_b32 s4, v254, 30
	v_readlane_b32 s5, v254, 31
	v_mul_f32_e32 v56, 0x3a800000, v46
	v_mov_b32_e32 v57, v0
	v_lshl_add_u64 v[48:49], v[44:45], 3, s[4:5]
	global_store_dwordx2 v[48:49], v[56:57], off
	s_and_b64 exec, exec, s[38:39]
	s_cbranch_execz .LBB0_149
	v_mul_f32_e32 v46, 0x3a800000, v43
	v_lshl_add_u64 v[48:49], s[42:43], 3, v[48:49]
	global_store_dwordx2 v[48:49], v[46:47], off
